# v044 + final RMSNorm of prompt rows fused into the last FFN-down epilogue (4-workgroup row-panel rendezvous), final phase only handles sample rows
# speedup vs baseline: 1.0096x; 1.0096x over previous
; __device__ __forceinline__ unsigned pk(float lo, float hi) { return pg8::cvt_pk_bf16(lo, hi); }
; __device__ __forceinline__ float dot4(f32x4 v) { return (v[0] * v[0] + v[1] * v[1]) + (v[2] * v[2] + v[3] * v[3]); }
;     __device__ __forceinline__ void operator()(const pg8::f32x4 (&acc)[2][2][4][2], const pg8::Unit& u, int wr, int wc, int fr, int fq) const {
;         const int row0 = u.pm * 256 + wr * 64 + fr;
; #pragma unroll
;         for (int ai = 0; ai < 2; ++ai)
; #pragma unroll
;             for (int m = 0; m < 4; ++m) {
;                 const int row = row0 + ai * 128 + m * 16;
;                 const float* xi = (row < MP) ? xin_p + (size_t)row * DM : xin_s + (size_t)(row - MP) * DM;
;                 float sq = 0.f;
; #pragma unroll
;                 for (int bj = 0; bj < 2; ++bj) { const int col = u.pn * 256 + bj * 128 + wc * 32 + 8 * fq;
;                     const f32x4 a0 = *(const f32x4*)(xi + col) + acc[ai][bj][m][0], a1 = *(const f32x4*)(xi + col + 4) + acc[ai][bj][m][1];
;                     *(f32x4*)(xout + (size_t)row * DM + col) = a0; *(f32x4*)(xout + (size_t)row * DM + col + 4) = a1;
;                     u32x4 w; w.x = pk(a0[0], a0[1]); w.y = pk(a0[2], a0[3]); w.z = pk(a1[0], a1[1]); w.w = pk(a1[2], a1[3]);
;                     *(u32x4*)(xb + (size_t)row * DM + col) = w;
;                     sq += dot4(a0) + dot4(a1); }
;                 sq += __shfl_xor(sq, 16); sq += __shfl_xor(sq, 32);
;                 if (fq == 0) atomicAdd(ssout + row, sq);
.LBB0_2089:
	s_cmp_lt_u32 s58, 64
	s_cselect_b32 s98, s16, s8
	s_cselect_b32 s99, s17, s9
	s_cselect_b32 s100, 0, 0x4000
	v_lshl_add_u32 v232, s58, 8, v163
	v_lshl_or_b32 v233, s57, 8, v164
	v_mov_b32_e32 v242, s58
	v_lshlrev_b32_e32 v242, 8, v242
	v_add_u32_e32 v242, 0x100000, v242
	v_lshlrev_b32_e32 v235, 2, v232
	v_lshlrev_b32_e32 v234, 2, v233
	v_lshl_add_u32 v236, v232, 12, v234
	v_subrev_u32_e32 v232, s100, v232
	v_lshl_add_u32 v237, v232, 12, v234
	global_load_dwordx4 v[168:171], v237, s[98:99]
	global_load_dwordx4 v[172:175], v237, s[98:99] offset:16
	global_load_dwordx4 v[176:179], v237, s[98:99] offset:512
	global_load_dwordx4 v[180:183], v237, s[98:99] offset:528
	v_add_u32_e32 v238, 0x10000, v237
	global_load_dwordx4 v[184:187], v238, s[98:99]
	global_load_dwordx4 v[188:191], v238, s[98:99] offset:16
	global_load_dwordx4 v[192:195], v238, s[98:99] offset:512
	global_load_dwordx4 v[196:199], v238, s[98:99] offset:528
	v_add_u32_e32 v238, 0x20000, v237
	global_load_dwordx4 v[200:203], v238, s[98:99]
	global_load_dwordx4 v[204:207], v238, s[98:99] offset:16
	global_load_dwordx4 v[208:211], v238, s[98:99] offset:512
	global_load_dwordx4 v[212:215], v238, s[98:99] offset:528
	v_add_u32_e32 v238, 0x30000, v237
	global_load_dwordx4 v[216:219], v238, s[98:99]
	global_load_dwordx4 v[220:223], v238, s[98:99] offset:16
	global_load_dwordx4 v[224:227], v238, s[98:99] offset:512
	global_load_dwordx4 v[228:231], v238, s[98:99] offset:528
	s_waitcnt vmcnt(12)
	v_pk_add_f32 v[126:127], v[126:127], v[168:169]
	v_pk_add_f32 v[128:129], v[128:129], v[170:171]
	v_pk_add_f32 v[122:123], v[122:123], v[172:173]
	v_pk_add_f32 v[124:125], v[124:125], v[174:175]
	v_pk_add_f32 v[118:119], v[118:119], v[176:177]
	v_pk_add_f32 v[120:121], v[120:121], v[178:179]
	v_pk_add_f32 v[114:115], v[114:115], v[180:181]
	v_pk_add_f32 v[116:117], v[116:117], v[182:183]
	v_mul_f32_e32 v176, v127, v127
	v_mul_f32_e32 v177, v129, v129
	v_mul_f32_e32 v178, v123, v123
	v_mul_f32_e32 v179, v125, v125
	v_fmac_f32_e32 v176, v126, v126
	v_fmac_f32_e32 v177, v128, v128
	v_fmac_f32_e32 v178, v122, v122
	v_fmac_f32_e32 v179, v124, v124
	v_add_f32_e32 v176, v176, v177
	v_add_f32_e32 v178, v178, v179
	v_add_f32_e32 v240, v176, v178
	v_mul_f32_e32 v176, v119, v119
	v_mul_f32_e32 v177, v121, v121
	v_mul_f32_e32 v178, v115, v115
	v_mul_f32_e32 v179, v117, v117
	v_fmac_f32_e32 v176, v118, v118
	v_fmac_f32_e32 v177, v120, v120
	v_fmac_f32_e32 v178, v114, v114
	v_fmac_f32_e32 v179, v116, v116
	v_add_f32_e32 v176, v176, v177
	v_add_f32_e32 v178, v178, v179
	v_add_f32_e32 v176, v176, v178
	v_add_f32_e32 v240, v240, v176
	v_mov_b32_e32 v241, v240
	s_nop 1
	v_permlane16_swap_b32_e32 v240, v241
	v_add_f32_e32 v240, v240, v241
	v_mov_b32_e32 v241, v240
	s_nop 1
	v_permlane32_swap_b32_e32 v240, v241
	v_add_f32_e32 v240, v240, v241
	s_mov_b64 exec, s[0:1]
	global_atomic_add_f32 v235, v240, s[10:11]
	s_mov_b64 exec, -1
	v_add_u32_e32 v238, 0x80000, v237
	global_load_dwordx4 v[168:171], v238, s[98:99]
	global_load_dwordx4 v[172:175], v238, s[98:99] offset:16
	global_load_dwordx4 v[176:179], v238, s[98:99] offset:512
	global_load_dwordx4 v[180:183], v238, s[98:99] offset:528
	s_waitcnt vmcnt(12)
	v_pk_add_f32 v[110:111], v[110:111], v[184:185]
	v_pk_add_f32 v[112:113], v[112:113], v[186:187]
	v_pk_add_f32 v[106:107], v[106:107], v[188:189]
	v_pk_add_f32 v[108:109], v[108:109], v[190:191]
	v_pk_add_f32 v[102:103], v[102:103], v[192:193]
	v_pk_add_f32 v[104:105], v[104:105], v[194:195]
	v_pk_add_f32 v[98:99], v[98:99], v[196:197]
	v_pk_add_f32 v[100:101], v[100:101], v[198:199]
	v_mul_f32_e32 v192, v111, v111
	v_mul_f32_e32 v193, v113, v113
	v_mul_f32_e32 v194, v107, v107
	v_mul_f32_e32 v195, v109, v109
	v_fmac_f32_e32 v192, v110, v110
	v_fmac_f32_e32 v193, v112, v112
	v_fmac_f32_e32 v194, v106, v106
	v_fmac_f32_e32 v195, v108, v108
	v_add_f32_e32 v192, v192, v193
	v_add_f32_e32 v194, v194, v195
	v_add_f32_e32 v240, v192, v194
	v_mul_f32_e32 v192, v103, v103
	v_mul_f32_e32 v193, v105, v105
	v_mul_f32_e32 v194, v99, v99
	v_mul_f32_e32 v195, v101, v101
	v_fmac_f32_e32 v192, v102, v102
	v_fmac_f32_e32 v193, v104, v104
	v_fmac_f32_e32 v194, v98, v98
	v_fmac_f32_e32 v195, v100, v100
	v_add_f32_e32 v192, v192, v193
	v_add_f32_e32 v194, v194, v195
	v_add_f32_e32 v192, v192, v194
	v_add_f32_e32 v240, v240, v192
	v_mov_b32_e32 v241, v240
	s_nop 1
	v_permlane16_swap_b32_e32 v240, v241
	v_add_f32_e32 v240, v240, v241
	v_mov_b32_e32 v241, v240
	s_nop 1
	v_permlane32_swap_b32_e32 v240, v241
	v_add_f32_e32 v240, v240, v241
	s_mov_b64 exec, s[0:1]
	global_atomic_add_f32 v235, v240, s[10:11] offset:64
	s_mov_b64 exec, -1
	v_add_u32_e32 v238, 0x90000, v237
	global_load_dwordx4 v[184:187], v238, s[98:99]
	global_load_dwordx4 v[188:191], v238, s[98:99] offset:16
	global_load_dwordx4 v[192:195], v238, s[98:99] offset:512
	global_load_dwordx4 v[196:199], v238, s[98:99] offset:528
	s_waitcnt vmcnt(12)
; __device__ __forceinline__ unsigned pk(float lo, float hi) { return pg8::cvt_pk_bf16(lo, hi); }
; __device__ __forceinline__ float dot4(f32x4 v) { return (v[0] * v[0] + v[1] * v[1]) + (v[2] * v[2] + v[3] * v[3]); }
;     __device__ __forceinline__ void operator()(const pg8::f32x4 (&acc)[2][2][4][2], const pg8::Unit& u, int wr, int wc, int fr, int fq) const {
;     ...
;             for (int m = 0; m < 4; ++m) {
;                 const int row = row0 + ai * 128 + m * 16;
;                 const float* xi = (row < MP) ? xin_p + (size_t)row * DM : xin_s + (size_t)(row - MP) * DM;
;                 float sq = 0.f;
; #pragma unroll
;                 for (int bj = 0; bj < 2; ++bj) { const int col = u.pn * 256 + bj * 128 + wc * 32 + 8 * fq;
;                     const f32x4 a0 = *(const f32x4*)(xi + col) + acc[ai][bj][m][0], a1 = *(const f32x4*)(xi + col + 4) + acc[ai][bj][m][1];
;                     *(f32x4*)(xout + (size_t)row * DM + col) = a0; *(f32x4*)(xout + (size_t)row * DM + col + 4) = a1;
;                     u32x4 w; w.x = pk(a0[0], a0[1]); w.y = pk(a0[2], a0[3]); w.z = pk(a1[0], a1[1]); w.w = pk(a1[2], a1[3]);
;                     *(u32x4*)(xb + (size_t)row * DM + col) = w;
;                     sq += dot4(a0) + dot4(a1); }
;                 sq += __shfl_xor(sq, 16); sq += __shfl_xor(sq, 32);
;                 if (fq == 0) atomicAdd(ssout + row, sq);
	v_pk_add_f32 v[94:95], v[94:95], v[200:201]
	v_pk_add_f32 v[96:97], v[96:97], v[202:203]
	v_pk_add_f32 v[90:91], v[90:91], v[204:205]
	v_pk_add_f32 v[92:93], v[92:93], v[206:207]
	v_pk_add_f32 v[86:87], v[86:87], v[208:209]
	v_pk_add_f32 v[88:89], v[88:89], v[210:211]
	v_pk_add_f32 v[82:83], v[82:83], v[212:213]
	v_pk_add_f32 v[84:85], v[84:85], v[214:215]
	v_mul_f32_e32 v208, v95, v95
	v_mul_f32_e32 v209, v97, v97
	v_mul_f32_e32 v210, v91, v91
	v_mul_f32_e32 v211, v93, v93
	v_fmac_f32_e32 v208, v94, v94
	v_fmac_f32_e32 v209, v96, v96
	v_fmac_f32_e32 v210, v90, v90
	v_fmac_f32_e32 v211, v92, v92
	v_add_f32_e32 v208, v208, v209
	v_add_f32_e32 v210, v210, v211
	v_add_f32_e32 v240, v208, v210
	v_mul_f32_e32 v208, v87, v87
	v_mul_f32_e32 v209, v89, v89
	v_mul_f32_e32 v210, v83, v83
	v_mul_f32_e32 v211, v85, v85
	v_fmac_f32_e32 v208, v86, v86
	v_fmac_f32_e32 v209, v88, v88
	v_fmac_f32_e32 v210, v82, v82
	v_fmac_f32_e32 v211, v84, v84
	v_add_f32_e32 v208, v208, v209
	v_add_f32_e32 v210, v210, v211
	v_add_f32_e32 v208, v208, v210
	v_add_f32_e32 v240, v240, v208
	v_mov_b32_e32 v241, v240
	s_nop 1
	v_permlane16_swap_b32_e32 v240, v241
	v_add_f32_e32 v240, v240, v241
	v_mov_b32_e32 v241, v240
	s_nop 1
	v_permlane32_swap_b32_e32 v240, v241
	v_add_f32_e32 v240, v240, v241
	s_mov_b64 exec, s[0:1]
	global_atomic_add_f32 v235, v240, s[10:11] offset:128
	s_mov_b64 exec, -1
	v_add_u32_e32 v238, 0xa0000, v237
	global_load_dwordx4 v[200:203], v238, s[98:99]
	global_load_dwordx4 v[204:207], v238, s[98:99] offset:16
	global_load_dwordx4 v[208:211], v238, s[98:99] offset:512
	global_load_dwordx4 v[212:215], v238, s[98:99] offset:528
	s_waitcnt vmcnt(12)
	v_pk_add_f32 v[78:79], v[78:79], v[216:217]
	v_pk_add_f32 v[80:81], v[80:81], v[218:219]
	v_pk_add_f32 v[74:75], v[74:75], v[220:221]
	v_pk_add_f32 v[76:77], v[76:77], v[222:223]
	v_pk_add_f32 v[70:71], v[70:71], v[224:225]
	v_pk_add_f32 v[72:73], v[72:73], v[226:227]
	v_pk_add_f32 v[66:67], v[66:67], v[228:229]
	v_pk_add_f32 v[68:69], v[68:69], v[230:231]
	v_mul_f32_e32 v224, v79, v79
	v_mul_f32_e32 v225, v81, v81
	v_mul_f32_e32 v226, v75, v75
	v_mul_f32_e32 v227, v77, v77
	v_fmac_f32_e32 v224, v78, v78
	v_fmac_f32_e32 v225, v80, v80
	v_fmac_f32_e32 v226, v74, v74
	v_fmac_f32_e32 v227, v76, v76
	v_add_f32_e32 v224, v224, v225
	v_add_f32_e32 v226, v226, v227
	v_add_f32_e32 v240, v224, v226
	v_mul_f32_e32 v224, v71, v71
	v_mul_f32_e32 v225, v73, v73
	v_mul_f32_e32 v226, v67, v67
	v_mul_f32_e32 v227, v69, v69
	v_fmac_f32_e32 v224, v70, v70
	v_fmac_f32_e32 v225, v72, v72
	v_fmac_f32_e32 v226, v66, v66
	v_fmac_f32_e32 v227, v68, v68
	v_add_f32_e32 v224, v224, v225
	v_add_f32_e32 v226, v226, v227
	v_add_f32_e32 v224, v224, v226
	v_add_f32_e32 v240, v240, v224
	v_mov_b32_e32 v241, v240
	s_nop 1
	v_permlane16_swap_b32_e32 v240, v241
	v_add_f32_e32 v240, v240, v241
	v_mov_b32_e32 v241, v240
	s_nop 1
	v_permlane32_swap_b32_e32 v240, v241
	v_add_f32_e32 v240, v240, v241
	s_mov_b64 exec, s[0:1]
	global_atomic_add_f32 v235, v240, s[10:11] offset:192
	s_mov_b64 exec, -1
	v_add_u32_e32 v238, 0xb0000, v237
	global_load_dwordx4 v[216:219], v238, s[98:99]
	global_load_dwordx4 v[220:223], v238, s[98:99] offset:16
	global_load_dwordx4 v[224:227], v238, s[98:99] offset:512
	global_load_dwordx4 v[228:231], v238, s[98:99] offset:528
	s_waitcnt vmcnt(12)
	v_pk_add_f32 v[62:63], v[62:63], v[168:169]
	v_pk_add_f32 v[64:65], v[64:65], v[170:171]
	v_pk_add_f32 v[58:59], v[58:59], v[172:173]
	v_pk_add_f32 v[60:61], v[60:61], v[174:175]
	v_pk_add_f32 v[54:55], v[54:55], v[176:177]
	v_pk_add_f32 v[56:57], v[56:57], v[178:179]
	v_pk_add_f32 v[50:51], v[50:51], v[180:181]
	v_pk_add_f32 v[52:53], v[52:53], v[182:183]
	v_mul_f32_e32 v176, v63, v63
	v_mul_f32_e32 v177, v65, v65
	v_mul_f32_e32 v178, v59, v59
	v_mul_f32_e32 v179, v61, v61
	v_fmac_f32_e32 v176, v62, v62
	v_fmac_f32_e32 v177, v64, v64
	v_fmac_f32_e32 v178, v58, v58
	v_fmac_f32_e32 v179, v60, v60
	v_add_f32_e32 v176, v176, v177
	v_add_f32_e32 v178, v178, v179
	v_add_f32_e32 v240, v176, v178
	v_mul_f32_e32 v176, v55, v55
	v_mul_f32_e32 v177, v57, v57
	v_mul_f32_e32 v178, v51, v51
	v_mul_f32_e32 v179, v53, v53
	v_fmac_f32_e32 v176, v54, v54
	v_fmac_f32_e32 v177, v56, v56
	v_fmac_f32_e32 v178, v50, v50
	v_fmac_f32_e32 v179, v52, v52
	v_add_f32_e32 v176, v176, v177
	v_add_f32_e32 v178, v178, v179
	v_add_f32_e32 v176, v176, v178
	v_add_f32_e32 v240, v240, v176
	v_mov_b32_e32 v241, v240
	s_nop 1
	v_permlane16_swap_b32_e32 v240, v241
	v_add_f32_e32 v240, v240, v241
	v_mov_b32_e32 v241, v240
	s_nop 1
	v_permlane32_swap_b32_e32 v240, v241
	v_add_f32_e32 v240, v240, v241
	s_mov_b64 exec, s[0:1]
	global_atomic_add_f32 v235, v240, s[10:11] offset:512
	s_mov_b64 exec, -1
	s_waitcnt vmcnt(8)
	v_pk_add_f32 v[46:47], v[46:47], v[184:185]
	v_pk_add_f32 v[48:49], v[48:49], v[186:187]
	v_pk_add_f32 v[42:43], v[42:43], v[188:189]
	v_pk_add_f32 v[44:45], v[44:45], v[190:191]
	v_pk_add_f32 v[38:39], v[38:39], v[192:193]
	v_pk_add_f32 v[40:41], v[40:41], v[194:195]
	v_pk_add_f32 v[34:35], v[34:35], v[196:197]
	v_pk_add_f32 v[36:37], v[36:37], v[198:199]
	v_mul_f32_e32 v192, v47, v47
	v_mul_f32_e32 v193, v49, v49
	v_mul_f32_e32 v194, v43, v43
	v_mul_f32_e32 v195, v45, v45
	v_fmac_f32_e32 v192, v46, v46
	v_fmac_f32_e32 v193, v48, v48
	v_fmac_f32_e32 v194, v42, v42
	v_fmac_f32_e32 v195, v44, v44
	v_add_f32_e32 v192, v192, v193
	v_add_f32_e32 v194, v194, v195
	v_add_f32_e32 v240, v192, v194
	v_mul_f32_e32 v192, v39, v39
	v_mul_f32_e32 v193, v41, v41
	v_mul_f32_e32 v194, v35, v35
	v_mul_f32_e32 v195, v37, v37
	v_fmac_f32_e32 v192, v38, v38
	v_fmac_f32_e32 v193, v40, v40
	v_fmac_f32_e32 v194, v34, v34
	v_fmac_f32_e32 v195, v36, v36
	v_add_f32_e32 v192, v192, v193
	v_add_f32_e32 v194, v194, v195
	v_add_f32_e32 v192, v192, v194
	v_add_f32_e32 v240, v240, v192
	v_mov_b32_e32 v241, v240
	s_nop 1
	v_permlane16_swap_b32_e32 v240, v241
	v_add_f32_e32 v240, v240, v241
	v_mov_b32_e32 v241, v240
	s_nop 1
	v_permlane32_swap_b32_e32 v240, v241
	v_add_f32_e32 v240, v240, v241
	s_mov_b64 exec, s[0:1]
	global_atomic_add_f32 v235, v240, s[10:11] offset:576
	s_mov_b64 exec, -1
	s_waitcnt vmcnt(4)
; __device__ __forceinline__ unsigned pk(float lo, float hi) { return pg8::cvt_pk_bf16(lo, hi); }
; __device__ __forceinline__ float dot4(f32x4 v) { return (v[0] * v[0] + v[1] * v[1]) + (v[2] * v[2] + v[3] * v[3]); }
; __device__ __forceinline__ void p_final(const Args& a, int vcu, int G) {
;     ...
;         for (int q = 0; q < 3; ++q) { const int m = m0 + q * NGW; if (m < MT) { rs[q] = rsqrtf(ss[m] * (1.f / DM) + EPS);
; #pragma unroll
;             for (int j = 0; j < 4; ++j) v[q][j] = __builtin_nontemporal_load((const f32x4*)(XR + (size_t)m * DM) + lane + 64 * j); } }
;     __device__ __forceinline__ void operator()(const pg8::f32x4 (&acc)[2][2][4][2], const pg8::Unit& u, int wr, int wc, int fr, int fq) const {
;     ...
;             for (int m = 0; m < 4; ++m) {
;                 const int row = row0 + ai * 128 + m * 16;
;                 const float* xi = (row < MP) ? xin_p + (size_t)row * DM : xin_s + (size_t)(row - MP) * DM;
;                 float sq = 0.f;
; #pragma unroll
;                 for (int bj = 0; bj < 2; ++bj) { const int col = u.pn * 256 + bj * 128 + wc * 32 + 8 * fq;
;                     const f32x4 a0 = *(const f32x4*)(xi + col) + acc[ai][bj][m][0], a1 = *(const f32x4*)(xi + col + 4) + acc[ai][bj][m][1];
;                     *(f32x4*)(xout + (size_t)row * DM + col) = a0; *(f32x4*)(xout + (size_t)row * DM + col + 4) = a1;
;                     u32x4 w; w.x = pk(a0[0], a0[1]); w.y = pk(a0[2], a0[3]); w.z = pk(a1[0], a1[1]); w.w = pk(a1[2], a1[3]);
;                     *(u32x4*)(xb + (size_t)row * DM + col) = w;
;                     sq += dot4(a0) + dot4(a1); }
;                 sq += __shfl_xor(sq, 16); sq += __shfl_xor(sq, 32);
;                 if (fq == 0) atomicAdd(ssout + row, sq);
	v_pk_add_f32 v[30:31], v[30:31], v[200:201]
	v_pk_add_f32 v[32:33], v[32:33], v[202:203]
	v_pk_add_f32 v[26:27], v[26:27], v[204:205]
	v_pk_add_f32 v[28:29], v[28:29], v[206:207]
	v_pk_add_f32 v[22:23], v[22:23], v[208:209]
	v_pk_add_f32 v[24:25], v[24:25], v[210:211]
	v_pk_add_f32 v[18:19], v[18:19], v[212:213]
	v_pk_add_f32 v[20:21], v[20:21], v[214:215]
	v_mul_f32_e32 v208, v31, v31
	v_mul_f32_e32 v209, v33, v33
	v_mul_f32_e32 v210, v27, v27
	v_mul_f32_e32 v211, v29, v29
	v_fmac_f32_e32 v208, v30, v30
	v_fmac_f32_e32 v209, v32, v32
	v_fmac_f32_e32 v210, v26, v26
	v_fmac_f32_e32 v211, v28, v28
	v_add_f32_e32 v208, v208, v209
	v_add_f32_e32 v210, v210, v211
	v_add_f32_e32 v240, v208, v210
	v_mul_f32_e32 v208, v23, v23
	v_mul_f32_e32 v209, v25, v25
	v_mul_f32_e32 v210, v19, v19
	v_mul_f32_e32 v211, v21, v21
	v_fmac_f32_e32 v208, v22, v22
	v_fmac_f32_e32 v209, v24, v24
	v_fmac_f32_e32 v210, v18, v18
	v_fmac_f32_e32 v211, v20, v20
	v_add_f32_e32 v208, v208, v209
	v_add_f32_e32 v210, v210, v211
	v_add_f32_e32 v208, v208, v210
	v_add_f32_e32 v240, v240, v208
	v_mov_b32_e32 v241, v240
	s_nop 1
	v_permlane16_swap_b32_e32 v240, v241
	v_add_f32_e32 v240, v240, v241
	v_mov_b32_e32 v241, v240
	s_nop 1
	v_permlane32_swap_b32_e32 v240, v241
	v_add_f32_e32 v240, v240, v241
	s_mov_b64 exec, s[0:1]
	global_atomic_add_f32 v235, v240, s[10:11] offset:640
	s_mov_b64 exec, -1
	s_waitcnt vmcnt(0)
	v_pk_add_f32 v[14:15], v[14:15], v[216:217]
	v_pk_add_f32 v[16:17], v[16:17], v[218:219]
	v_pk_add_f32 v[10:11], v[10:11], v[220:221]
	v_pk_add_f32 v[12:13], v[12:13], v[222:223]
	v_pk_add_f32 v[6:7], v[6:7], v[224:225]
	v_pk_add_f32 v[8:9], v[8:9], v[226:227]
	v_pk_add_f32 v[2:3], v[2:3], v[228:229]
	v_pk_add_f32 v[4:5], v[4:5], v[230:231]
	v_mul_f32_e32 v224, v15, v15
	v_mul_f32_e32 v225, v17, v17
	v_mul_f32_e32 v226, v11, v11
	v_mul_f32_e32 v227, v13, v13
	v_fmac_f32_e32 v224, v14, v14
	v_fmac_f32_e32 v225, v16, v16
	v_fmac_f32_e32 v226, v10, v10
	v_fmac_f32_e32 v227, v12, v12
	v_add_f32_e32 v224, v224, v225
	v_add_f32_e32 v226, v226, v227
	v_add_f32_e32 v240, v224, v226
	v_mul_f32_e32 v224, v7, v7
	v_mul_f32_e32 v225, v9, v9
	v_mul_f32_e32 v226, v3, v3
	v_mul_f32_e32 v227, v5, v5
	v_fmac_f32_e32 v224, v6, v6
	v_fmac_f32_e32 v225, v8, v8
	v_fmac_f32_e32 v226, v2, v2
	v_fmac_f32_e32 v227, v4, v4
	v_add_f32_e32 v224, v224, v225
	v_add_f32_e32 v226, v226, v227
	v_add_f32_e32 v224, v224, v226
	v_add_f32_e32 v240, v240, v224
	v_mov_b32_e32 v241, v240
	s_nop 1
	v_permlane16_swap_b32_e32 v240, v241
	v_add_f32_e32 v240, v240, v241
	v_mov_b32_e32 v241, v240
	s_nop 1
	v_permlane32_swap_b32_e32 v240, v241
	v_add_f32_e32 v240, v240, v241
	s_mov_b64 exec, s[0:1]
	global_atomic_add_f32 v235, v240, s[10:11] offset:704
	s_mov_b64 exec, -1
	s_waitcnt vmcnt(0)
	s_barrier
	v_readlane_b32 s98, v252, 4
	v_readlane_b32 s99, v252, 5
	v_readlane_b32 s100, v252, 6
	v_readlane_b32 s101, v252, 7
	v_cmp_eq_u32_e32 vcc, 0, v0
	s_nop 1
	s_mov_b64 exec, vcc
	s_cbranch_execz .Lfin_join
	v_mov_b32_e32 v243, 1
	global_atomic_add v242, v243, s[28:29]
	s_waitcnt vmcnt(0)
	v_mov_b32_e32 v247, 0
.Lfin_spin:
	global_load_dword v244, v242, s[28:29] sc1
	s_waitcnt vmcnt(0)
	v_cmp_gt_u32_e32 vcc, 4, v244
	s_cbranch_vccz .Lfin_join
	s_sleep 1
	v_add_u32_e32 v247, 1, v247
	v_cmp_gt_u32_e32 vcc, 0x8000, v247
	s_cbranch_vccnz .Lfin_spin
.Lfin_join:
	s_mov_b64 exec, -1
	s_barrier
	v_lshlrev_b32_e32 v234, 2, v233
	global_load_dwordx4 v[184:187], v234, s[98:99]
	global_load_dwordx4 v[188:191], v234, s[98:99] offset:16
	global_load_dwordx4 v[192:195], v234, s[98:99] offset:512
	global_load_dwordx4 v[196:199], v234, s[98:99] offset:528
	global_load_dword v168, v235, s[10:11] sc1
	global_load_dword v170, v235, s[10:11] offset:64 sc1
	global_load_dword v172, v235, s[10:11] offset:128 sc1
	global_load_dword v174, v235, s[10:11] offset:192 sc1
	global_load_dword v176, v235, s[10:11] offset:512 sc1
	global_load_dword v178, v235, s[10:11] offset:576 sc1
	global_load_dword v180, v235, s[10:11] offset:640 sc1
	global_load_dword v182, v235, s[10:11] offset:704 sc1
	v_mov_b32_e32 v246, 0x358637bd
	s_waitcnt vmcnt(0)
	v_fmamk_f32 v168, v168, 0x3a800000, v246
	v_fmamk_f32 v170, v170, 0x3a800000, v246
	v_fmamk_f32 v172, v172, 0x3a800000, v246
	v_fmamk_f32 v174, v174, 0x3a800000, v246
	v_fmamk_f32 v176, v176, 0x3a800000, v246
	v_fmamk_f32 v178, v178, 0x3a800000, v246
	v_fmamk_f32 v180, v180, 0x3a800000, v246
	v_fmamk_f32 v182, v182, 0x3a800000, v246
	v_mul_f32_e32 v245, 0x4b800000, v168
	v_cmp_gt_f32_e32 vcc, 0x800000, v168
	s_nop 1
	v_cndmask_b32_e32 v168, v168, v245, vcc
	v_rsq_f32_e32 v168, v168
	s_nop 0
	v_mul_f32_e32 v245, 0x45800000, v168
	v_cndmask_b32_e32 v168, v168, v245, vcc
	v_mul_f32_e32 v245, 0x4b800000, v170
	v_cmp_gt_f32_e32 vcc, 0x800000, v170
	s_nop 1
	v_cndmask_b32_e32 v170, v170, v245, vcc
	v_rsq_f32_e32 v170, v170
	s_nop 0
	v_mul_f32_e32 v245, 0x45800000, v170
	v_cndmask_b32_e32 v170, v170, v245, vcc
	v_mul_f32_e32 v245, 0x4b800000, v172
	v_cmp_gt_f32_e32 vcc, 0x800000, v172
	s_nop 1
	v_cndmask_b32_e32 v172, v172, v245, vcc
	v_rsq_f32_e32 v172, v172
	s_nop 0
	v_mul_f32_e32 v245, 0x45800000, v172
	v_cndmask_b32_e32 v172, v172, v245, vcc
	v_mul_f32_e32 v245, 0x4b800000, v174
	v_cmp_gt_f32_e32 vcc, 0x800000, v174
	s_nop 1
	v_cndmask_b32_e32 v174, v174, v245, vcc
	v_rsq_f32_e32 v174, v174
	s_nop 0
	v_mul_f32_e32 v245, 0x45800000, v174
	v_cndmask_b32_e32 v174, v174, v245, vcc
	v_mul_f32_e32 v245, 0x4b800000, v176
	v_cmp_gt_f32_e32 vcc, 0x800000, v176
	s_nop 1
	v_cndmask_b32_e32 v176, v176, v245, vcc
	v_rsq_f32_e32 v176, v176
	s_nop 0
	v_mul_f32_e32 v245, 0x45800000, v176
	v_cndmask_b32_e32 v176, v176, v245, vcc
; __device__ __forceinline__ void p_final(const Args& a, int vcu, int G) {
;     ...
;         for (int q = 0; q < 3; ++q) { const int m = m0 + q * NGW; if (m < MT) { rs[q] = rsqrtf(ss[m] * (1.f / DM) + EPS);
; #pragma unroll
;             for (int j = 0; j < 4; ++j) v[q][j] = __builtin_nontemporal_load((const f32x4*)(XR + (size_t)m * DM) + lane + 64 * j); } }
; #pragma unroll
;         for (int q = 0; q < 3; ++q) { const int m = m0 + q * NGW; if (m < MT) {
; #pragma unroll
;             for (int j = 0; j < 4; ++j) __builtin_nontemporal_store(v[q][j] * rs[q] * gv[j], (f32x4*)(a.out + O_Y + (size_t)m * DM) + lane + 64 * j); } }
	v_mul_f32_e32 v245, 0x4b800000, v178
	v_cmp_gt_f32_e32 vcc, 0x800000, v178
	s_nop 1
	v_cndmask_b32_e32 v178, v178, v245, vcc
	v_rsq_f32_e32 v178, v178
	s_nop 0
	v_mul_f32_e32 v245, 0x45800000, v178
	v_cndmask_b32_e32 v178, v178, v245, vcc
	v_mul_f32_e32 v245, 0x4b800000, v180
	v_cmp_gt_f32_e32 vcc, 0x800000, v180
	s_nop 1
	v_cndmask_b32_e32 v180, v180, v245, vcc
	v_rsq_f32_e32 v180, v180
	s_nop 0
	v_mul_f32_e32 v245, 0x45800000, v180
	v_cndmask_b32_e32 v180, v180, v245, vcc
	v_mul_f32_e32 v245, 0x4b800000, v182
	v_cmp_gt_f32_e32 vcc, 0x800000, v182
	s_nop 1
	v_cndmask_b32_e32 v182, v182, v245, vcc
	v_rsq_f32_e32 v182, v182
	s_nop 0
	v_mul_f32_e32 v245, 0x45800000, v182
	v_cndmask_b32_e32 v182, v182, v245, vcc
	v_pk_mul_f32 v[126:127], v[126:127], v[168:169] op_sel_hi:[1,0]
	v_pk_mul_f32 v[128:129], v[128:129], v[168:169] op_sel_hi:[1,0]
	v_pk_mul_f32 v[126:127], v[126:127], v[184:185]
	v_pk_mul_f32 v[128:129], v[128:129], v[186:187]
	v_pk_mul_f32 v[122:123], v[122:123], v[168:169] op_sel_hi:[1,0]
	v_pk_mul_f32 v[124:125], v[124:125], v[168:169] op_sel_hi:[1,0]
	v_pk_mul_f32 v[122:123], v[122:123], v[188:189]
	v_pk_mul_f32 v[124:125], v[124:125], v[190:191]
	v_pk_mul_f32 v[118:119], v[118:119], v[168:169] op_sel_hi:[1,0]
	v_pk_mul_f32 v[120:121], v[120:121], v[168:169] op_sel_hi:[1,0]
	v_pk_mul_f32 v[118:119], v[118:119], v[192:193]
	v_pk_mul_f32 v[120:121], v[120:121], v[194:195]
	v_pk_mul_f32 v[114:115], v[114:115], v[168:169] op_sel_hi:[1,0]
	v_pk_mul_f32 v[116:117], v[116:117], v[168:169] op_sel_hi:[1,0]
	v_pk_mul_f32 v[114:115], v[114:115], v[196:197]
	v_pk_mul_f32 v[116:117], v[116:117], v[198:199]
	global_store_dwordx4 v236, v[126:129], s[100:101] nt
	global_store_dwordx4 v236, v[122:125], s[100:101] offset:16 nt
	global_store_dwordx4 v236, v[118:121], s[100:101] offset:512 nt
	global_store_dwordx4 v236, v[114:117], s[100:101] offset:528 nt
	v_pk_mul_f32 v[110:111], v[110:111], v[170:171] op_sel_hi:[1,0]
	v_pk_mul_f32 v[112:113], v[112:113], v[170:171] op_sel_hi:[1,0]
	v_pk_mul_f32 v[110:111], v[110:111], v[184:185]
	v_pk_mul_f32 v[112:113], v[112:113], v[186:187]
	v_pk_mul_f32 v[106:107], v[106:107], v[170:171] op_sel_hi:[1,0]
	v_pk_mul_f32 v[108:109], v[108:109], v[170:171] op_sel_hi:[1,0]
	v_pk_mul_f32 v[106:107], v[106:107], v[188:189]
	v_pk_mul_f32 v[108:109], v[108:109], v[190:191]
	v_pk_mul_f32 v[102:103], v[102:103], v[170:171] op_sel_hi:[1,0]
	v_pk_mul_f32 v[104:105], v[104:105], v[170:171] op_sel_hi:[1,0]
	v_pk_mul_f32 v[102:103], v[102:103], v[192:193]
	v_pk_mul_f32 v[104:105], v[104:105], v[194:195]
	v_pk_mul_f32 v[98:99], v[98:99], v[170:171] op_sel_hi:[1,0]
	v_pk_mul_f32 v[100:101], v[100:101], v[170:171] op_sel_hi:[1,0]
	v_pk_mul_f32 v[98:99], v[98:99], v[196:197]
	v_pk_mul_f32 v[100:101], v[100:101], v[198:199]
	v_add_u32_e32 v239, 0x10000, v236
	global_store_dwordx4 v239, v[110:113], s[100:101] nt
	global_store_dwordx4 v239, v[106:109], s[100:101] offset:16 nt
	global_store_dwordx4 v239, v[102:105], s[100:101] offset:512 nt
	global_store_dwordx4 v239, v[98:101], s[100:101] offset:528 nt
	v_pk_mul_f32 v[94:95], v[94:95], v[172:173] op_sel_hi:[1,0]
	v_pk_mul_f32 v[96:97], v[96:97], v[172:173] op_sel_hi:[1,0]
	v_pk_mul_f32 v[94:95], v[94:95], v[184:185]
	v_pk_mul_f32 v[96:97], v[96:97], v[186:187]
	v_pk_mul_f32 v[90:91], v[90:91], v[172:173] op_sel_hi:[1,0]
	v_pk_mul_f32 v[92:93], v[92:93], v[172:173] op_sel_hi:[1,0]
	v_pk_mul_f32 v[90:91], v[90:91], v[188:189]
	v_pk_mul_f32 v[92:93], v[92:93], v[190:191]
	v_pk_mul_f32 v[86:87], v[86:87], v[172:173] op_sel_hi:[1,0]
	v_pk_mul_f32 v[88:89], v[88:89], v[172:173] op_sel_hi:[1,0]
	v_pk_mul_f32 v[86:87], v[86:87], v[192:193]
	v_pk_mul_f32 v[88:89], v[88:89], v[194:195]
	v_pk_mul_f32 v[82:83], v[82:83], v[172:173] op_sel_hi:[1,0]
	v_pk_mul_f32 v[84:85], v[84:85], v[172:173] op_sel_hi:[1,0]
	v_pk_mul_f32 v[82:83], v[82:83], v[196:197]
	v_pk_mul_f32 v[84:85], v[84:85], v[198:199]
	v_add_u32_e32 v239, 0x20000, v236
	global_store_dwordx4 v239, v[94:97], s[100:101] nt
	global_store_dwordx4 v239, v[90:93], s[100:101] offset:16 nt
	global_store_dwordx4 v239, v[86:89], s[100:101] offset:512 nt
	global_store_dwordx4 v239, v[82:85], s[100:101] offset:528 nt
	v_pk_mul_f32 v[78:79], v[78:79], v[174:175] op_sel_hi:[1,0]
	v_pk_mul_f32 v[80:81], v[80:81], v[174:175] op_sel_hi:[1,0]
	v_pk_mul_f32 v[78:79], v[78:79], v[184:185]
	v_pk_mul_f32 v[80:81], v[80:81], v[186:187]
	v_pk_mul_f32 v[74:75], v[74:75], v[174:175] op_sel_hi:[1,0]
	v_pk_mul_f32 v[76:77], v[76:77], v[174:175] op_sel_hi:[1,0]
	v_pk_mul_f32 v[74:75], v[74:75], v[188:189]
	v_pk_mul_f32 v[76:77], v[76:77], v[190:191]
	v_pk_mul_f32 v[70:71], v[70:71], v[174:175] op_sel_hi:[1,0]
	v_pk_mul_f32 v[72:73], v[72:73], v[174:175] op_sel_hi:[1,0]
	v_pk_mul_f32 v[70:71], v[70:71], v[192:193]
	v_pk_mul_f32 v[72:73], v[72:73], v[194:195]
	v_pk_mul_f32 v[66:67], v[66:67], v[174:175] op_sel_hi:[1,0]
	v_pk_mul_f32 v[68:69], v[68:69], v[174:175] op_sel_hi:[1,0]
	v_pk_mul_f32 v[66:67], v[66:67], v[196:197]
; __device__ __forceinline__ void p_final(const Args& a, int vcu, int G) {
;     ...
;         for (int q = 0; q < 3; ++q) { const int m = m0 + q * NGW; if (m < MT) {
; #pragma unroll
;             for (int j = 0; j < 4; ++j) __builtin_nontemporal_store(v[q][j] * rs[q] * gv[j], (f32x4*)(a.out + O_Y + (size_t)m * DM) + lane + 64 * j); } }
	v_pk_mul_f32 v[68:69], v[68:69], v[198:199]
	v_add_u32_e32 v239, 0x30000, v236
	global_store_dwordx4 v239, v[78:81], s[100:101] nt
	global_store_dwordx4 v239, v[74:77], s[100:101] offset:16 nt
	global_store_dwordx4 v239, v[70:73], s[100:101] offset:512 nt
	global_store_dwordx4 v239, v[66:69], s[100:101] offset:528 nt
	v_pk_mul_f32 v[62:63], v[62:63], v[176:177] op_sel_hi:[1,0]
	v_pk_mul_f32 v[64:65], v[64:65], v[176:177] op_sel_hi:[1,0]
	v_pk_mul_f32 v[62:63], v[62:63], v[184:185]
	v_pk_mul_f32 v[64:65], v[64:65], v[186:187]
	v_pk_mul_f32 v[58:59], v[58:59], v[176:177] op_sel_hi:[1,0]
	v_pk_mul_f32 v[60:61], v[60:61], v[176:177] op_sel_hi:[1,0]
	v_pk_mul_f32 v[58:59], v[58:59], v[188:189]
	v_pk_mul_f32 v[60:61], v[60:61], v[190:191]
	v_pk_mul_f32 v[54:55], v[54:55], v[176:177] op_sel_hi:[1,0]
	v_pk_mul_f32 v[56:57], v[56:57], v[176:177] op_sel_hi:[1,0]
	v_pk_mul_f32 v[54:55], v[54:55], v[192:193]
	v_pk_mul_f32 v[56:57], v[56:57], v[194:195]
	v_pk_mul_f32 v[50:51], v[50:51], v[176:177] op_sel_hi:[1,0]
	v_pk_mul_f32 v[52:53], v[52:53], v[176:177] op_sel_hi:[1,0]
	v_pk_mul_f32 v[50:51], v[50:51], v[196:197]
	v_pk_mul_f32 v[52:53], v[52:53], v[198:199]
	v_add_u32_e32 v239, 0x80000, v236
	global_store_dwordx4 v239, v[62:65], s[100:101] nt
	global_store_dwordx4 v239, v[58:61], s[100:101] offset:16 nt
	global_store_dwordx4 v239, v[54:57], s[100:101] offset:512 nt
	global_store_dwordx4 v239, v[50:53], s[100:101] offset:528 nt
	v_pk_mul_f32 v[46:47], v[46:47], v[178:179] op_sel_hi:[1,0]
	v_pk_mul_f32 v[48:49], v[48:49], v[178:179] op_sel_hi:[1,0]
	v_pk_mul_f32 v[46:47], v[46:47], v[184:185]
	v_pk_mul_f32 v[48:49], v[48:49], v[186:187]
	v_pk_mul_f32 v[42:43], v[42:43], v[178:179] op_sel_hi:[1,0]
	v_pk_mul_f32 v[44:45], v[44:45], v[178:179] op_sel_hi:[1,0]
	v_pk_mul_f32 v[42:43], v[42:43], v[188:189]
	v_pk_mul_f32 v[44:45], v[44:45], v[190:191]
	v_pk_mul_f32 v[38:39], v[38:39], v[178:179] op_sel_hi:[1,0]
	v_pk_mul_f32 v[40:41], v[40:41], v[178:179] op_sel_hi:[1,0]
	v_pk_mul_f32 v[38:39], v[38:39], v[192:193]
	v_pk_mul_f32 v[40:41], v[40:41], v[194:195]
	v_pk_mul_f32 v[34:35], v[34:35], v[178:179] op_sel_hi:[1,0]
	v_pk_mul_f32 v[36:37], v[36:37], v[178:179] op_sel_hi:[1,0]
	v_pk_mul_f32 v[34:35], v[34:35], v[196:197]
	v_pk_mul_f32 v[36:37], v[36:37], v[198:199]
	v_add_u32_e32 v239, 0x90000, v236
	global_store_dwordx4 v239, v[46:49], s[100:101] nt
	global_store_dwordx4 v239, v[42:45], s[100:101] offset:16 nt
	global_store_dwordx4 v239, v[38:41], s[100:101] offset:512 nt
	global_store_dwordx4 v239, v[34:37], s[100:101] offset:528 nt
	v_pk_mul_f32 v[30:31], v[30:31], v[180:181] op_sel_hi:[1,0]
	v_pk_mul_f32 v[32:33], v[32:33], v[180:181] op_sel_hi:[1,0]
	v_pk_mul_f32 v[30:31], v[30:31], v[184:185]
	v_pk_mul_f32 v[32:33], v[32:33], v[186:187]
	v_pk_mul_f32 v[26:27], v[26:27], v[180:181] op_sel_hi:[1,0]
	v_pk_mul_f32 v[28:29], v[28:29], v[180:181] op_sel_hi:[1,0]
	v_pk_mul_f32 v[26:27], v[26:27], v[188:189]
	v_pk_mul_f32 v[28:29], v[28:29], v[190:191]
	v_pk_mul_f32 v[22:23], v[22:23], v[180:181] op_sel_hi:[1,0]
	v_pk_mul_f32 v[24:25], v[24:25], v[180:181] op_sel_hi:[1,0]
	v_pk_mul_f32 v[22:23], v[22:23], v[192:193]
	v_pk_mul_f32 v[24:25], v[24:25], v[194:195]
	v_pk_mul_f32 v[18:19], v[18:19], v[180:181] op_sel_hi:[1,0]
	v_pk_mul_f32 v[20:21], v[20:21], v[180:181] op_sel_hi:[1,0]
	v_pk_mul_f32 v[18:19], v[18:19], v[196:197]
	v_pk_mul_f32 v[20:21], v[20:21], v[198:199]
	v_add_u32_e32 v239, 0xa0000, v236
	global_store_dwordx4 v239, v[30:33], s[100:101] nt
	global_store_dwordx4 v239, v[26:29], s[100:101] offset:16 nt
	global_store_dwordx4 v239, v[22:25], s[100:101] offset:512 nt
	global_store_dwordx4 v239, v[18:21], s[100:101] offset:528 nt
	v_pk_mul_f32 v[14:15], v[14:15], v[182:183] op_sel_hi:[1,0]
	v_pk_mul_f32 v[16:17], v[16:17], v[182:183] op_sel_hi:[1,0]
	v_pk_mul_f32 v[14:15], v[14:15], v[184:185]
	v_pk_mul_f32 v[16:17], v[16:17], v[186:187]
	v_pk_mul_f32 v[10:11], v[10:11], v[182:183] op_sel_hi:[1,0]
	v_pk_mul_f32 v[12:13], v[12:13], v[182:183] op_sel_hi:[1,0]
	v_pk_mul_f32 v[10:11], v[10:11], v[188:189]
	v_pk_mul_f32 v[12:13], v[12:13], v[190:191]
	v_pk_mul_f32 v[6:7], v[6:7], v[182:183] op_sel_hi:[1,0]
	v_pk_mul_f32 v[8:9], v[8:9], v[182:183] op_sel_hi:[1,0]
	v_pk_mul_f32 v[6:7], v[6:7], v[192:193]
	v_pk_mul_f32 v[8:9], v[8:9], v[194:195]
	v_pk_mul_f32 v[2:3], v[2:3], v[182:183] op_sel_hi:[1,0]
	v_pk_mul_f32 v[4:5], v[4:5], v[182:183] op_sel_hi:[1,0]
	v_pk_mul_f32 v[2:3], v[2:3], v[196:197]
	v_pk_mul_f32 v[4:5], v[4:5], v[198:199]
	v_add_u32_e32 v239, 0xb0000, v236
	global_store_dwordx4 v239, v[14:17], s[100:101] nt
	global_store_dwordx4 v239, v[10:13], s[100:101] offset:16 nt
	global_store_dwordx4 v239, v[6:9], s[100:101] offset:512 nt
	global_store_dwordx4 v239, v[2:5], s[100:101] offset:528 nt
	s_and_b64 vcc, exec, s[4:5]
	s_mov_b64 s[4:5], -1
	s_cbranch_vccnz .LBB0_2074
	s_andn2_b64 vcc, exec, s[18:19]
	s_cbranch_vccnz .LBB0_2073
	s_barrier
	s_branch .LBB0_2073

; __device__ __forceinline__ void p_final(const Args& a, int vcu, int G) {
;     const int tid = threadIdx.x, lane = tid & 63, wave = tid >> 6;
;     const int gw = vcu * 8 + wave, NGW = G * 8;
;     const float* ss = (const float*)(a.ws + WS_SS + 4 * 131072);
;     const float* XR = (const float*)(a.ws + WS_XR);
;     const float* g = a.in[I_NFIN];
;     f32x4 gv[4];
; #pragma unroll
;     for (int j = 0; j < 4; ++j) gv[j] = ((const f32x4*)g)[lane + 64 * j];
;     for (int m0 = gw; m0 < MT; m0 += 3 * NGW) {
;         f32x4 v[3][4]; float rs[3];
; #pragma unroll
;         for (int q = 0; q < 3; ++q) { const int m = m0 + q * NGW; if (m < MT) { rs[q] = rsqrtf(ss[m] * (1.f / DM) + EPS);
.LBB0_2258:
	s_cmp_lt_i32 s30, 15
	s_cselect_b64 s[0:1], -1, 0
	s_cmp_gt_i32 s31, 14
	s_cselect_b64 s[2:3], -1, 0
	s_and_b64 s[0:1], s[0:1], s[2:3]
	s_andn2_b64 vcc, exec, s[0:1]
	s_cbranch_vccnz .LBB0_2270
	v_lshl_or_b32 v74, s96, 3, v1
	v_add_u32_e32 v74, 0x4000, v74
	s_movk_i32 s12, 0x4800
	v_cmp_gt_i32_e32 vcc, s12, v74
	s_and_saveexec_b64 s[0:1], vcc
	s_cbranch_execz .LBB0_2270
	v_readlane_b32 s0, v252, 0
	v_readlane_b32 s6, v252, 6
	v_readlane_b32 s7, v252, 7
	v_and_b32_e32 v0, 63, v0
	v_readlane_b32 s4, v252, 4
	v_readlane_b32 s5, v252, 5
	s_mov_b64 s[10:11], s[6:7]
	v_lshlrev_b32_e32 v16, 4, v0
	s_mov_b64 s[8:9], s[4:5]
	s_waitcnt lgkmcnt(0)
	global_load_dwordx4 v[0:3], v16, s[8:9]
	global_load_dwordx4 v[4:7], v16, s[8:9] offset:1024
	global_load_dwordx4 v[8:11], v16, s[8:9] offset:2048
	global_load_dwordx4 v[12:15], v16, s[8:9] offset:3072
	s_add_u32 s4, s28, 0x90000
	s_addc_u32 s5, s29, 0
	v_mov_b32_e32 v17, 0
	s_lshl_b32 s6, s34, 3
	v_lshl_add_u64 v[64:65], s[16:17], 0, v[16:17]
	s_waitcnt vmcnt(4)
	v_lshl_add_u64 v[66:67], s[10:11], 0, v[16:17]
	s_ashr_i32 s7, s6, 31
	s_lshl_b32 s13, s34, 4
	s_mov_b64 s[8:9], 0
	v_mov_b32_e32 v69, 0x358637bd
	s_mov_b32 s14, 0x800000
	s_add_i32 s15, s6, s6
	s_movk_i32 s16, 0x47ff
	v_readlane_b32 s1, v252, 1
	v_readlane_b32 s2, v252, 2
	v_readlane_b32 s3, v252, 3
	s_branch .LBB0_2262
